# stream unit: per-workgroup rotation of the in-page sub-tile order (de-phases the streaming CUs' in-page offsets)
# baseline (speedup 1.0000x reference)
.LBB0_538:
	s_or_b64 exec, exec, s[0:1]
	s_ashr_i32 s7, s20, 3
	s_ashr_i32 s4, s23, 8
	s_lshl_b32 s98, s4, 1
	s_add_i32 s98, s98, s20
	s_and_b32 s98, s98, 3
	s_lshl_b32 s99, s98, 7
	s_lshl_b32 s98, s98, 5
	s_lshl_b32 s0, s7, 6
	s_ashr_i32 s1, s0, 31
	s_lshl_b32 s26, s4, 2
	s_and_b32 s6, s20, 7
	s_ashr_i32 s27, s26, 31
	s_lshl_b64 s[0:1], s[0:1], 2
	s_add_u32 s0, s76, s0
	s_addc_u32 s1, s77, s1
	s_lshl_b32 s23, s6, 5
	s_add_u32 s23, s0, s23
	s_addc_u32 s28, s1, 0
	s_lshl_b32 s0, s22, 14
	s_add_i32 s25, s0, 0
	s_lshl_b64 s[0:1], s[26:27], 2
	s_add_u32 s0, s23, s0
	s_addc_u32 s1, s28, s1
	global_load_dword v18, v183, s[0:1]
	v_bfe_u32 v19, v20, 4, 2
	v_and_b32_e32 v192, 63, v20
	v_lshlrev_b32_e32 v103, 3, v20
	v_lshrrev_b32_e32 v21, 2, v190
	v_lshlrev_b32_e32 v191, 2, v19
	s_waitcnt vmcnt(39)
	v_xor_b32_e32 v22, v19, v190
	v_bitop3_b32 v23, v19, v190, 4 bitop3:0x36
	v_bitop3_b32 v24, v19, v190, 8 bitop3:0x36
	v_bitop3_b32 v25, v19, v190, 12 bitop3:0x36
	v_and_b32_e32 v105, 24, v103
	v_lshrrev_b32_e32 v182, 5, v192
	v_or_b32_e32 v19, v191, v21
	v_lshl_or_b32 v122, v19, 8, v105
	v_lshlrev_b32_e32 v19, 5, v19
	s_movk_i32 s23, 0xe0
	v_and_b32_e32 v123, 0xe0, v19
	v_bitop3_b32 v124, v19, s23, v122 bitop3:0x26
	v_and_b32_e32 v102, 31, v20
	v_bfe_u32 v104, v20, 2, 3
	v_lshlrev_b32_e32 v20, 8, v190
	v_lshl_or_b32 v114, v22, 4, v20
	v_lshl_or_b32 v115, v23, 4, v20
	v_lshl_or_b32 v116, v24, 4, v20
	v_lshl_or_b32 v117, v25, 4, v20
	v_or_b32_e32 v178, 10, v182
	v_lshl_add_u32 v181, v178, 8, s25
	v_lshlrev_b32_e32 v184, 4, v178
	v_bitop3_b32 v178, v178, v104, 3 bitop3:0x6c
	v_lshl_add_u32 v205, v178, 5, v181
	v_or_b32_e32 v178, 12, v182
	v_bitop3_b32 v186, v184, v103, s19 bitop3:0x78
	v_lshl_add_u32 v206, v178, 8, s25
	v_lshlrev_b32_e32 v184, 4, v178
	v_bitop3_b32 v178, v178, v104, 5 bitop3:0x6c
	v_lshl_add_u32 v208, v178, 5, v206
	v_or_b32_e32 v178, 14, v182
	v_or_b32_e32 v131, 4, v182
	v_or_b32_e32 v134, 6, v182
	v_or_b32_e32 v137, 8, v182
	v_bitop3_b32 v207, v184, v103, s19 bitop3:0x78
	v_lshl_add_u32 v209, v178, 8, s25
	v_lshlrev_b32_e32 v184, 4, v178
	v_bitop3_b32 v178, v178, v104, 7 bitop3:0x6c
	v_lshl_add_u32 v132, v131, 8, s25
	v_lshlrev_b32_e32 v131, 4, v131
	v_lshl_add_u32 v135, v134, 8, s25
	v_lshlrev_b32_e32 v134, 4, v134
	v_lshl_add_u32 v179, v137, 8, s25
	v_lshlrev_b32_e32 v137, 4, v137
	v_lshl_add_u32 v210, v178, 5, v209
	v_or_b32_e32 v178, 18, v182
	v_bitop3_b32 v131, v131, v103, s19 bitop3:0x78
	v_bitop3_b32 v134, v134, v103, s19 bitop3:0x78
	v_bitop3_b32 v137, v137, v103, s19 bitop3:0x78
	v_lshl_add_u32 v211, v178, 8, s25
	s_movk_i32 s23, 0x60
	v_bitop3_b32 v127, v123, s23, v122 bitop3:0x36
	s_movk_i32 s23, 0x80
	v_bitop3_b32 v128, v123, s23, v122 bitop3:0x36
	s_movk_i32 s23, 0xa0
	v_bitop3_b32 v129, v123, s23, v122 bitop3:0x36
	s_movk_i32 s23, 0xc0
	v_bitop3_b32 v133, v182, v104, 4 bitop3:0x36
	v_bitop3_b32 v136, v182, v104, 6 bitop3:0x36
	v_bitop3_b32 v125, v123, 32, v122 bitop3:0x36
	v_bitop3_b32 v126, v123, 64, v122 bitop3:0x36
	v_bitop3_b32 v130, v123, s23, v122 bitop3:0x36
	s_lshl_b32 s23, s21, 7
	v_lshl_add_u32 v133, v133, 5, v132
	v_lshl_add_u32 v136, v136, 5, v135
	v_add_u32_e32 v123, s25, v123
	s_mov_b32 s22, 32
	v_add_u32_e32 v198, v132, v131
	v_add_u32_e32 v199, v133, v105
	v_add_u32_e32 v200, v135, v134
	v_add_u32_e32 v201, v136, v105
	v_add_u32_e32 v202, v179, v137
	v_add_u32_e32 v204, v181, v186
	v_add_u32_e32 v205, v205, v105
	s_waitcnt vmcnt(0)
	v_readfirstlane_b32 s26, v18
	s_ashr_i32 s27, s26, 31
	s_lshl_b64 s[26:27], s[26:27], 9
	s_or_b32 s26, s26, s99
	v_lshl_or_b32 v18, v182, 2, s26
	v_mov_b32_e32 v19, s27
	v_or_b32_e32 v18, s21, v18
	v_lshlrev_b64 v[18:19], 9, v[18:19]
	v_lshl_or_b32 v18, v102, 4, v18
	v_lshl_add_u64 v[94:95], s[72:73], 0, v[18:19]
	v_add_co_u32_e32 v30, vcc, s11, v94
	v_lshl_add_u64 v[96:97], s[74:75], 0, v[18:19]
	s_nop 0
	v_addc_co_u32_e32 v31, vcc, 0, v95, vcc
	v_add_co_u32_e32 v38, vcc, s11, v96
	global_load_dwordx4 v[18:21], v[94:95], off nt
	global_load_dwordx4 v[22:25], v[96:97], off nt
	v_addc_co_u32_e32 v39, vcc, 0, v97, vcc
	v_add_co_u32_e32 v46, vcc, s10, v94
	s_movk_i32 s26, 0x50
	s_nop 0
	v_addc_co_u32_e32 v47, vcc, 0, v95, vcc
	v_add_co_u32_e32 v54, vcc, s10, v96
	v_add_u32_e32 v206, v206, v207
	s_nop 0
	v_addc_co_u32_e32 v55, vcc, 0, v97, vcc
	v_add_co_u32_e32 v62, vcc, s12, v94
	v_add_u32_e32 v207, v208, v105
	s_nop 0
	v_addc_co_u32_e32 v63, vcc, 0, v95, vcc
	v_add_co_u32_e32 v70, vcc, s12, v96
	v_add_u32_e32 v234, s25, v125
	s_nop 0
	v_addc_co_u32_e32 v71, vcc, 0, v97, vcc
	v_add_co_u32_e32 v78, vcc, s13, v94
	global_load_dwordx4 v[26:29], v[30:31], off offset:-4096 nt
	s_nop 0
	global_load_dwordx4 v[30:33], v[30:31], off nt
	s_nop 0
	global_load_dwordx4 v[34:37], v[38:39], off offset:-4096 nt
	s_nop 0
	global_load_dwordx4 v[38:41], v[38:39], off nt
	s_nop 0
	global_load_dwordx4 v[42:45], v[46:47], off offset:-4096 nt
	s_nop 0
	global_load_dwordx4 v[46:49], v[46:47], off nt
	s_nop 0
	global_load_dwordx4 v[50:53], v[54:55], off offset:-4096 nt
	s_nop 0
	global_load_dwordx4 v[54:57], v[54:55], off nt
	s_nop 0
	global_load_dwordx4 v[58:61], v[62:63], off offset:-4096 nt
	s_nop 0
	global_load_dwordx4 v[62:65], v[62:63], off nt
	s_nop 0
	global_load_dwordx4 v[66:69], v[70:71], off offset:-4096 nt
	s_nop 0
	global_load_dwordx4 v[70:73], v[70:71], off nt
	v_addc_co_u32_e32 v79, vcc, 0, v95, vcc
	v_add_co_u32_e32 v86, vcc, s13, v96
	v_add_u32_e32 v235, s25, v126
	s_nop 0
	v_addc_co_u32_e32 v87, vcc, 0, v97, vcc
	v_add_co_u32_e32 v98, vcc, s14, v94
	global_load_dwordx4 v[74:77], v[78:79], off offset:-4096 nt
	s_nop 0
	global_load_dwordx4 v[78:81], v[78:79], off nt
	s_nop 0
	global_load_dwordx4 v[82:85], v[86:87], off offset:-4096 nt
	s_nop 0
	global_load_dwordx4 v[86:89], v[86:87], off nt
	v_addc_co_u32_e32 v99, vcc, 0, v95, vcc
	v_add_co_u32_e32 v100, vcc, s14, v96
	v_add_u32_e32 v236, s25, v127
	s_nop 0
	v_addc_co_u32_e32 v101, vcc, 0, v97, vcc
	global_load_dwordx4 v[90:93], v[98:99], off offset:-4096 nt
	global_load_dwordx4 v[106:109], v[98:99], off nt
	global_load_dwordx4 v[110:113], v[100:101], off offset:-4096 nt
	global_load_dwordx4 v[118:121], v[100:101], off nt
	v_add_co_u32_e32 v98, vcc, s15, v94
	v_add_u32_e32 v237, s25, v128
	s_nop 0
	v_addc_co_u32_e32 v99, vcc, 0, v95, vcc
	v_add_co_u32_e32 v100, vcc, s15, v96
	v_add_u32_e32 v238, s25, v129
	s_nop 0
	v_addc_co_u32_e32 v101, vcc, 0, v97, vcc
	global_load_dwordx4 v[138:141], v[98:99], off offset:-4096 nt
	global_load_dwordx4 v[146:149], v[98:99], off nt
	global_load_dwordx4 v[142:145], v[100:101], off offset:-4096 nt
	global_load_dwordx4 v[150:153], v[100:101], off nt
	v_add_co_u32_e32 v98, vcc, s17, v94
	v_add_u32_e32 v239, s25, v130
	s_nop 0
	v_addc_co_u32_e32 v99, vcc, 0, v95, vcc
	v_add_co_u32_e32 v100, vcc, s17, v96
	v_add_u32_e32 v240, s25, v124
	s_nop 0
	v_addc_co_u32_e32 v101, vcc, 0, v97, vcc
	v_add_co_u32_e32 v94, vcc, s18, v94
	global_load_dwordx4 v[154:157], v[98:99], off offset:-4096 nt
	global_load_dwordx4 v[162:165], v[98:99], off nt
	global_load_dwordx4 v[158:161], v[100:101], off offset:-4096 nt
	global_load_dwordx4 v[166:169], v[100:101], off nt
	v_addc_co_u32_e32 v95, vcc, 0, v95, vcc
	global_load_dwordx4 v[170:173], v[94:95], off nt
	v_add_co_u32_e32 v94, vcc, s18, v96
	v_or_b32_e32 v99, 2, v182
	s_nop 0
	v_addc_co_u32_e32 v95, vcc, 0, v97, vcc
	global_load_dwordx4 v[174:177], v[94:95], off nt
	v_lshlrev_b32_e32 v96, 4, v182
	v_lshl_add_u32 v100, v99, 8, s25
	v_lshlrev_b32_e32 v99, 4, v99
	v_and_b32_e32 v94, 0xf8, v103
	v_bitop3_b32 v96, v103, v96, s19 bitop3:0x6c
	v_bitop3_b32 v99, v99, v103, s19 bitop3:0x78
	v_bitop3_b32 v103, v184, v103, s19 bitop3:0x78
	v_lshlrev_b32_e32 v184, 4, v178
	v_bitop3_b32 v178, v178, v104, 3 bitop3:0x6c
	v_lshl_add_u32 v213, v178, 5, v211
	v_or_b32_e32 v178, 20, v182
	v_bitop3_b32 v212, v184, v94, 48 bitop3:0x6c
	v_lshl_add_u32 v214, v178, 8, s25
	v_lshlrev_b32_e32 v184, 4, v178
	v_bitop3_b32 v178, v178, v104, 5 bitop3:0x6c
	v_lshl_add_u32 v216, v178, 5, v214
	v_or_b32_e32 v178, 22, v182
	v_bitop3_b32 v215, v184, v94, s26 bitop3:0x6c
	v_lshl_add_u32 v217, v178, 8, s25
	v_lshlrev_b32_e32 v184, 4, v178
	v_bitop3_b32 v178, v178, v104, 7 bitop3:0x6c
	s_movk_i32 s26, 0x70
	v_lshl_add_u32 v219, v178, 5, v217
	v_or_b32_e32 v178, 24, v182
	v_bitop3_b32 v218, v184, v94, s26 bitop3:0x6c
	v_lshl_add_u32 v220, v178, 8, s25
	v_lshlrev_b32_e32 v178, 4, v178
	s_movk_i32 s26, 0x90
	v_bitop3_b32 v221, v178, v94, s26 bitop3:0x6c
	v_or_b32_e32 v178, 26, v182
	v_lshl_add_u32 v227, v178, 8, s25
	v_lshlrev_b32_e32 v184, 4, v178
	v_bitop3_b32 v178, v178, v104, 3 bitop3:0x6c
	s_movk_i32 s26, 0xb0
	v_lshl_add_u32 v229, v178, 5, v227
	v_or_b32_e32 v178, 28, v182
	v_bitop3_b32 v228, v184, v94, s26 bitop3:0x6c
	v_lshl_add_u32 v230, v178, 8, s25
	v_lshlrev_b32_e32 v184, 4, v178
	v_bitop3_b32 v178, v178, v104, 5 bitop3:0x6c
	v_xor_b32_e32 v97, v182, v104
	s_movk_i32 s26, 0xd0
	v_lshl_add_u32 v232, v178, 5, v230
	v_or_b32_e32 v178, 30, v182
	v_lshl_add_u32 v95, v182, 8, s25
	v_lshlrev_b32_e32 v97, 5, v97
	v_bitop3_b32 v101, v182, v104, 2 bitop3:0x36
	v_bitop3_b32 v231, v184, v94, s26 bitop3:0x6c
	v_lshl_add_u32 v233, v178, 8, s25
	v_lshlrev_b32_e32 v184, 4, v178
	s_movk_i32 s26, 0xf0
	v_bitop3_b32 v104, v178, v104, 7 bitop3:0x6c
	v_add_u32_e32 v98, v95, v97
	v_lshl_add_u32 v101, v101, 5, v100
	v_add_u32_e32 v180, v179, v97
	v_add_u32_e32 v97, v220, v97
	v_bitop3_b32 v94, v184, v94, s26 bitop3:0x6c
	v_lshl_add_u32 v104, v104, 5, v233
	v_lshl_or_b32 v184, v102, 2, s23
	v_mov_b32_e32 v178, 0xf149f2ca
	v_add_u32_e32 v194, v95, v96
	v_add_u32_e32 v195, v98, v105
	v_add_u32_e32 v196, v100, v99
	v_add_u32_e32 v197, v101, v105
	v_add_u32_e32 v203, v180, v105
	v_add_u32_e32 v208, v209, v103
	v_add_u32_e32 v209, v210, v105
	v_add_u32_e32 v210, v211, v212
	v_add_u32_e32 v211, v213, v105
	v_add_u32_e32 v212, v214, v215
	v_add_u32_e32 v213, v216, v105
	v_add_u32_e32 v214, v217, v218
	v_add_u32_e32 v215, v219, v105
	v_add_u32_e32 v216, v220, v221
	v_add_u32_e32 v217, v97, v105
	v_add_u32_e32 v218, v227, v228
	v_add_u32_e32 v219, v229, v105
	v_add_u32_e32 v220, v230, v231
	v_add_u32_e32 v221, v232, v105
	v_add_u32_e32 v227, v233, v94
	v_add_u32_e32 v228, v104, v105
	s_lshl_b32 s23, s23, 2
	v_add_u32_e32 v229, s25, v114
	v_add_u32_e32 v230, s25, v115
	v_add_u32_e32 v231, s25, v116
	v_add_u32_e32 v232, s25, v117
	v_add_u32_e32 v233, v123, v122
	v_mov_b32_e32 v94, 0
	v_mov_b32_e32 v95, v193
	v_mov_b32_e32 v96, v193
	v_mov_b32_e32 v97, v193
	v_mov_b32_e32 v98, 0
	v_mov_b32_e32 v99, v193
	v_mov_b32_e32 v100, v193
	v_mov_b32_e32 v101, v193
	v_mov_b32_e32 v102, 0
	v_mov_b32_e32 v103, v193
	v_mov_b32_e32 v104, v193
	v_mov_b32_e32 v105, v193
	v_mov_b32_e32 v114, 0
	v_mov_b32_e32 v115, v193
	v_mov_b32_e32 v116, v193
	v_mov_b32_e32 v117, v193
	v_mov_b32_e32 v122, 0
	v_mov_b32_e32 v123, v193
	v_mov_b32_e32 v124, v193
	v_mov_b32_e32 v125, v193
	v_mov_b32_e32 v126, 0
	v_mov_b32_e32 v127, v193
	v_mov_b32_e32 v128, v193
	v_mov_b32_e32 v129, v193
	v_mov_b32_e32 v130, 0
	v_mov_b32_e32 v131, v193
	v_mov_b32_e32 v132, v193
	v_mov_b32_e32 v133, v193
	v_mov_b32_e32 v134, 0
	v_mov_b32_e32 v135, v193
	v_mov_b32_e32 v136, v193
	v_mov_b32_e32 v137, v193
.LBB0_539:
	s_waitcnt vmcnt(29)
	v_cvt_pk_bf16_f32 v244, v26, v27
	v_cvt_pk_bf16_f32 v245, v28, v29
	ds_write_b64 v196, v[244:245]
	s_waitcnt vmcnt(27)
	v_cvt_pk_bf16_f32 v244, v34, v35
	v_cvt_pk_bf16_f32 v245, v36, v37
	ds_write_b64 v197, v[244:245] offset:8192
	v_cvt_pk_bf16_f32 v244, v30, v31
	v_cvt_pk_bf16_f32 v245, v32, v33
	ds_write_b64 v198, v[244:245]
	s_waitcnt vmcnt(26)
	v_cvt_pk_bf16_f32 v244, v38, v39
	v_cvt_pk_bf16_f32 v245, v40, v41
	ds_write_b64 v199, v[244:245] offset:8192
	s_waitcnt vmcnt(25)
	v_cvt_pk_bf16_f32 v244, v42, v43
	v_cvt_pk_bf16_f32 v245, v44, v45
	ds_write_b64 v200, v[244:245]
	s_waitcnt vmcnt(23)
	v_cvt_pk_bf16_f32 v244, v50, v51
	v_cvt_pk_bf16_f32 v245, v52, v53
	ds_write_b64 v201, v[244:245] offset:8192
	v_cvt_pk_bf16_f32 v244, v46, v47
	v_cvt_pk_bf16_f32 v245, v48, v49
	ds_write_b64 v202, v[244:245]
	s_waitcnt vmcnt(22)
	v_cvt_pk_bf16_f32 v244, v54, v55
	v_cvt_pk_bf16_f32 v245, v56, v57
	ds_write_b64 v203, v[244:245] offset:8192
	s_waitcnt vmcnt(21)
	v_cvt_pk_bf16_f32 v244, v58, v59
	v_cvt_pk_bf16_f32 v245, v60, v61
	ds_write_b64 v204, v[244:245]
	s_waitcnt vmcnt(19)
	v_cvt_pk_bf16_f32 v244, v66, v67
	v_cvt_pk_bf16_f32 v245, v68, v69
	ds_write_b64 v205, v[244:245] offset:8192
	v_cvt_pk_bf16_f32 v244, v62, v63
	v_cvt_pk_bf16_f32 v245, v64, v65
	ds_write_b64 v206, v[244:245]
	s_waitcnt vmcnt(18)
	v_cvt_pk_bf16_f32 v244, v70, v71
	v_cvt_pk_bf16_f32 v245, v72, v73
	ds_write_b64 v207, v[244:245] offset:8192
	s_waitcnt vmcnt(17)
	v_cvt_pk_bf16_f32 v244, v74, v75
	v_cvt_pk_bf16_f32 v245, v76, v77
	ds_write_b64 v208, v[244:245]
	s_waitcnt vmcnt(15)
	v_cvt_pk_bf16_f32 v244, v82, v83
	v_cvt_pk_bf16_f32 v245, v84, v85
	v_cvt_pk_bf16_f32 v180, v18, v19
	v_cvt_pk_bf16_f32 v181, v20, v21
	ds_write_b64 v209, v[244:245] offset:8192
	v_cvt_pk_bf16_f32 v244, v78, v79
	v_cvt_pk_bf16_f32 v245, v80, v81
	v_cvt_pk_bf16_f32 v242, v22, v23
	v_cvt_pk_bf16_f32 v243, v24, v25
	ds_write2st64_b64 v194, v[180:181], v[244:245] offset1:8
	s_waitcnt vmcnt(14)
	v_cvt_pk_bf16_f32 v180, v86, v87
	v_cvt_pk_bf16_f32 v181, v88, v89
	ds_write2st64_b64 v195, v[242:243], v[180:181] offset0:16 offset1:24
	s_waitcnt vmcnt(13)
	v_cvt_pk_bf16_f32 v180, v90, v91
	v_cvt_pk_bf16_f32 v181, v92, v93
	ds_write_b64 v210, v[180:181]
	s_waitcnt vmcnt(11)
	v_cvt_pk_bf16_f32 v180, v110, v111
	v_cvt_pk_bf16_f32 v181, v112, v113
	ds_write_b64 v211, v[180:181] offset:8192
	v_cvt_pk_bf16_f32 v180, v106, v107
	v_cvt_pk_bf16_f32 v181, v108, v109
	ds_write_b64 v212, v[180:181]
	s_waitcnt vmcnt(10)
	v_cvt_pk_bf16_f32 v180, v118, v119
	v_cvt_pk_bf16_f32 v181, v120, v121
	ds_write_b64 v213, v[180:181] offset:8192
	s_waitcnt vmcnt(9)
	v_cvt_pk_bf16_f32 v180, v138, v139
	v_cvt_pk_bf16_f32 v181, v140, v141
	ds_write_b64 v214, v[180:181]
	s_waitcnt vmcnt(7)
	v_cvt_pk_bf16_f32 v180, v142, v143
	v_cvt_pk_bf16_f32 v181, v144, v145
	ds_write_b64 v215, v[180:181] offset:8192
	v_cvt_pk_bf16_f32 v180, v146, v147
	v_cvt_pk_bf16_f32 v181, v148, v149
	ds_write_b64 v216, v[180:181]
	s_waitcnt vmcnt(6)
	v_cvt_pk_bf16_f32 v180, v150, v151
	v_cvt_pk_bf16_f32 v181, v152, v153
	ds_write_b64 v217, v[180:181] offset:8192
	s_waitcnt vmcnt(5)
	v_cvt_pk_bf16_f32 v180, v154, v155
	v_cvt_pk_bf16_f32 v181, v156, v157
	ds_write_b64 v218, v[180:181]
	s_waitcnt vmcnt(3)
	v_cvt_pk_bf16_f32 v180, v158, v159
	v_cvt_pk_bf16_f32 v181, v160, v161
	ds_write_b64 v219, v[180:181] offset:8192
	v_cvt_pk_bf16_f32 v180, v162, v163
	v_cvt_pk_bf16_f32 v181, v164, v165
	ds_write_b64 v220, v[180:181]
	s_waitcnt vmcnt(2)
	v_cvt_pk_bf16_f32 v180, v166, v167
	v_cvt_pk_bf16_f32 v181, v168, v169
	ds_write_b64 v221, v[180:181] offset:8192
	s_waitcnt vmcnt(1)
	v_cvt_pk_bf16_f32 v180, v170, v171
	v_cvt_pk_bf16_f32 v181, v172, v173
	s_add_i32 s25, s24, 1
	ds_write_b64 v227, v[180:181]
	s_waitcnt vmcnt(0)
	v_cvt_pk_bf16_f32 v180, v174, v175
	v_cvt_pk_bf16_f32 v181, v176, v177
	s_cmp_lg_u32 s24, 15
	ds_write_b64 v228, v[180:181] offset:8192
	s_cbranch_scc0 .LBB0_541
	s_and_b32 s26, s25, -4
	v_mov_b32_e32 v18, s26
	global_load_dword v18, v18, s[0:1]
	s_add_i32 s28, s22, s98
	s_and_b32 s28, s28, 0x60
	s_waitcnt vmcnt(0)
	v_readfirstlane_b32 s26, v18
	s_ashr_i32 s27, s26, 31
	s_lshl_b64 s[26:27], s[26:27], 7
	s_or_b32 s26, s26, s28
	v_mov_b32_e32 v19, s27
	v_or_b32_e32 v18, s26, v182
	v_lshlrev_b64 v[18:19], 11, v[18:19]
	v_lshl_or_b32 v18, v184, 2, v18
	v_lshl_add_u64 v[170:171], s[72:73], 0, v[18:19]
	v_add_co_u32_e32 v30, vcc, s11, v170
	v_lshl_add_u64 v[174:175], s[74:75], 0, v[18:19]
	s_nop 0
	v_addc_co_u32_e32 v31, vcc, 0, v171, vcc
	v_add_co_u32_e32 v38, vcc, s11, v174
	global_load_dwordx4 v[18:21], v[170:171], off nt
	global_load_dwordx4 v[22:25], v[174:175], off nt
	v_addc_co_u32_e32 v39, vcc, 0, v175, vcc
	v_add_co_u32_e32 v46, vcc, s10, v170
	global_load_dwordx4 v[26:29], v[30:31], off offset:-4096 nt
	s_nop 0
	v_addc_co_u32_e32 v47, vcc, 0, v171, vcc
	v_add_co_u32_e32 v54, vcc, s10, v174
	global_load_dwordx4 v[34:37], v[38:39], off offset:-4096 nt
	s_nop 0
	global_load_dwordx4 v[30:33], v[30:31], off nt
	s_nop 0
	global_load_dwordx4 v[38:41], v[38:39], off nt
	v_addc_co_u32_e32 v55, vcc, 0, v175, vcc
	v_add_co_u32_e32 v62, vcc, s12, v170
	global_load_dwordx4 v[42:45], v[46:47], off offset:-4096 nt
	s_nop 0
	v_addc_co_u32_e32 v63, vcc, 0, v171, vcc
	v_add_co_u32_e32 v70, vcc, s12, v174
	global_load_dwordx4 v[50:53], v[54:55], off offset:-4096 nt
	s_nop 0
	global_load_dwordx4 v[46:49], v[46:47], off nt
	s_nop 0
	global_load_dwordx4 v[54:57], v[54:55], off nt
	v_addc_co_u32_e32 v71, vcc, 0, v175, vcc
	v_add_co_u32_e32 v78, vcc, s13, v170
	global_load_dwordx4 v[58:61], v[62:63], off offset:-4096 nt
	s_nop 0
	v_addc_co_u32_e32 v79, vcc, 0, v171, vcc
	v_add_co_u32_e32 v86, vcc, s13, v174
	global_load_dwordx4 v[66:69], v[70:71], off offset:-4096 nt
	s_nop 0
	global_load_dwordx4 v[62:65], v[62:63], off nt
	s_nop 0
	global_load_dwordx4 v[70:73], v[70:71], off nt
	v_addc_co_u32_e32 v87, vcc, 0, v175, vcc
	v_add_co_u32_e32 v106, vcc, s14, v170
	global_load_dwordx4 v[74:77], v[78:79], off offset:-4096 nt
	s_nop 0
	v_addc_co_u32_e32 v107, vcc, 0, v171, vcc
	v_add_co_u32_e32 v118, vcc, s14, v174
	global_load_dwordx4 v[82:85], v[86:87], off offset:-4096 nt
	s_nop 0
	global_load_dwordx4 v[78:81], v[78:79], off nt
	s_nop 0
	global_load_dwordx4 v[86:89], v[86:87], off nt
	v_addc_co_u32_e32 v119, vcc, 0, v175, vcc
	v_add_co_u32_e32 v146, vcc, s15, v170
	global_load_dwordx4 v[90:93], v[106:107], off offset:-4096 nt
	s_nop 0
	v_addc_co_u32_e32 v147, vcc, 0, v171, vcc
	v_add_co_u32_e32 v150, vcc, s15, v174
	global_load_dwordx4 v[110:113], v[118:119], off offset:-4096 nt
	s_nop 0
	global_load_dwordx4 v[106:109], v[106:107], off nt
	s_nop 0
	global_load_dwordx4 v[118:121], v[118:119], off nt
	v_addc_co_u32_e32 v151, vcc, 0, v175, vcc
	v_add_co_u32_e32 v154, vcc, s16, v170
	global_load_dwordx4 v[138:141], v[146:147], off offset:-4096 nt
	s_nop 0
	v_addc_co_u32_e32 v155, vcc, 0, v171, vcc
	v_add_co_u32_e32 v158, vcc, s16, v174
	global_load_dwordx4 v[142:145], v[150:151], off offset:-4096 nt
	s_nop 0
	global_load_dwordx4 v[146:149], v[146:147], off nt
	s_nop 0
	global_load_dwordx4 v[150:153], v[150:151], off nt
	v_addc_co_u32_e32 v159, vcc, 0, v175, vcc
	v_add_co_u32_e32 v162, vcc, 0xe000, v170
	global_load_dwordx4 v[154:157], v[154:155], off nt
	s_nop 0
	v_addc_co_u32_e32 v163, vcc, 0, v171, vcc
	v_add_co_u32_e32 v166, vcc, 0xe000, v174
	global_load_dwordx4 v[158:161], v[158:159], off nt
	s_nop 0
	v_addc_co_u32_e32 v167, vcc, 0, v175, vcc
	v_add_co_u32_e32 v170, vcc, 0xf000, v170
	global_load_dwordx4 v[162:165], v[162:163], off nt
	s_nop 0
	v_addc_co_u32_e32 v171, vcc, 0, v171, vcc
	v_add_co_u32_e32 v174, vcc, 0xf000, v174
	global_load_dwordx4 v[166:169], v[166:167], off nt
	s_nop 0
	v_addc_co_u32_e32 v175, vcc, 0, v175, vcc
	global_load_dwordx4 v[170:173], v[170:171], off nt
	s_nop 0
	global_load_dwordx4 v[174:177], v[174:175], off nt

.LBB0_595:
	s_or_b64 exec, exec, s[0:1]
	s_ashr_i32 s7, s20, 3
	s_ashr_i32 s4, s23, 8
	s_lshl_b32 s98, s4, 1
	s_add_i32 s98, s98, s20
	s_and_b32 s98, s98, 3
	s_lshl_b32 s99, s98, 7
	s_lshl_b32 s98, s98, 5
	s_lshl_b32 s0, s7, 6
	s_ashr_i32 s1, s0, 31
	s_lshl_b32 s26, s4, 2
	s_and_b32 s6, s20, 7
	s_ashr_i32 s27, s26, 31
	s_lshl_b64 s[0:1], s[0:1], 2
	s_add_u32 s0, s76, s0
	s_addc_u32 s1, s77, s1
	s_lshl_b32 s23, s6, 5
	s_add_u32 s23, s0, s23
	s_addc_u32 s28, s1, 0
	s_lshl_b32 s0, s22, 14
	s_add_i32 s25, s0, 0
	s_lshl_b64 s[0:1], s[26:27], 2
	s_add_u32 s0, s23, s0
	s_addc_u32 s1, s28, s1
	global_load_dword v18, v183, s[0:1]
	v_bfe_u32 v19, v20, 4, 2
	v_and_b32_e32 v188, 63, v20
	v_lshlrev_b32_e32 v103, 3, v20
	v_lshrrev_b32_e32 v21, 2, v185
	v_lshlrev_b32_e32 v187, 2, v19
	s_waitcnt vmcnt(39)
	v_xor_b32_e32 v22, v19, v185
	v_bitop3_b32 v23, v19, v185, 4 bitop3:0x36
	v_bitop3_b32 v24, v19, v185, 8 bitop3:0x36
	v_bitop3_b32 v25, v19, v185, 12 bitop3:0x36
	v_and_b32_e32 v105, 24, v103
	v_lshrrev_b32_e32 v182, 5, v188
	v_or_b32_e32 v19, v187, v21
	v_lshl_or_b32 v122, v19, 8, v105
	v_lshlrev_b32_e32 v19, 5, v19
	s_movk_i32 s23, 0xe0
	v_and_b32_e32 v123, 0xe0, v19
	v_bitop3_b32 v124, v19, s23, v122 bitop3:0x26
	v_and_b32_e32 v102, 31, v20
	v_bfe_u32 v104, v20, 2, 3
	v_lshlrev_b32_e32 v20, 8, v185
	v_lshl_or_b32 v114, v22, 4, v20
	v_lshl_or_b32 v115, v23, 4, v20
	v_lshl_or_b32 v116, v24, 4, v20
	v_lshl_or_b32 v117, v25, 4, v20
	v_or_b32_e32 v178, 10, v182
	v_lshl_add_u32 v181, v178, 8, s25
	v_lshlrev_b32_e32 v184, 4, v178
	v_bitop3_b32 v178, v178, v104, 3 bitop3:0x6c
	v_lshl_add_u32 v202, v178, 5, v181
	v_or_b32_e32 v178, 12, v182
	v_bitop3_b32 v186, v184, v103, s19 bitop3:0x78
	v_lshl_add_u32 v203, v178, 8, s25
	v_lshlrev_b32_e32 v184, 4, v178
	v_bitop3_b32 v178, v178, v104, 5 bitop3:0x6c
	v_lshl_add_u32 v205, v178, 5, v203
	v_or_b32_e32 v178, 14, v182
	v_or_b32_e32 v131, 4, v182
	v_or_b32_e32 v134, 6, v182
	v_or_b32_e32 v137, 8, v182
	v_bitop3_b32 v204, v184, v103, s19 bitop3:0x78
	v_lshl_add_u32 v206, v178, 8, s25
	v_lshlrev_b32_e32 v184, 4, v178
	v_bitop3_b32 v178, v178, v104, 7 bitop3:0x6c
	v_lshl_add_u32 v132, v131, 8, s25
	v_lshlrev_b32_e32 v131, 4, v131
	v_lshl_add_u32 v135, v134, 8, s25
	v_lshlrev_b32_e32 v134, 4, v134
	v_lshl_add_u32 v179, v137, 8, s25
	v_lshlrev_b32_e32 v137, 4, v137
	v_lshl_add_u32 v207, v178, 5, v206
	v_or_b32_e32 v178, 18, v182
	v_bitop3_b32 v131, v131, v103, s19 bitop3:0x78
	v_bitop3_b32 v134, v134, v103, s19 bitop3:0x78
	v_bitop3_b32 v137, v137, v103, s19 bitop3:0x78
	v_lshl_add_u32 v208, v178, 8, s25
	s_movk_i32 s23, 0x60
	v_bitop3_b32 v127, v123, s23, v122 bitop3:0x36
	s_movk_i32 s23, 0x80
	v_bitop3_b32 v128, v123, s23, v122 bitop3:0x36
	s_movk_i32 s23, 0xa0
	v_bitop3_b32 v129, v123, s23, v122 bitop3:0x36
	s_movk_i32 s23, 0xc0
	v_bitop3_b32 v133, v182, v104, 4 bitop3:0x36
	v_bitop3_b32 v136, v182, v104, 6 bitop3:0x36
	v_bitop3_b32 v125, v123, 32, v122 bitop3:0x36
	v_bitop3_b32 v126, v123, 64, v122 bitop3:0x36
	v_bitop3_b32 v130, v123, s23, v122 bitop3:0x36
	s_lshl_b32 s23, s21, 7
	v_lshl_add_u32 v133, v133, 5, v132
	v_lshl_add_u32 v136, v136, 5, v135
	v_add_u32_e32 v123, s25, v123
	s_mov_b32 s22, 32
	v_add_u32_e32 v194, v132, v131
	v_add_u32_e32 v195, v133, v105
	v_add_u32_e32 v197, v135, v134
	v_add_u32_e32 v198, v136, v105
	v_add_u32_e32 v199, v179, v137
	v_add_u32_e32 v201, v181, v186
	v_add_u32_e32 v202, v202, v105
	s_waitcnt vmcnt(0)
	v_readfirstlane_b32 s26, v18
	s_ashr_i32 s27, s26, 31
	s_lshl_b64 s[26:27], s[26:27], 9
	s_or_b32 s26, s26, s99
	v_lshl_or_b32 v18, v182, 2, s26
	v_mov_b32_e32 v19, s27
	v_or_b32_e32 v18, s21, v18
	v_lshlrev_b64 v[18:19], 9, v[18:19]
	v_lshl_or_b32 v18, v102, 4, v18
	v_lshl_add_u64 v[94:95], s[72:73], 0, v[18:19]
	v_add_co_u32_e32 v30, vcc, s11, v94
	v_lshl_add_u64 v[96:97], s[74:75], 0, v[18:19]
	s_nop 0
	v_addc_co_u32_e32 v31, vcc, 0, v95, vcc
	v_add_co_u32_e32 v38, vcc, s11, v96
	global_load_dwordx4 v[18:21], v[94:95], off nt
	global_load_dwordx4 v[22:25], v[96:97], off nt
	v_addc_co_u32_e32 v39, vcc, 0, v97, vcc
	v_add_co_u32_e32 v46, vcc, s10, v94
	s_movk_i32 s26, 0x50
	s_nop 0
	v_addc_co_u32_e32 v47, vcc, 0, v95, vcc
	v_add_co_u32_e32 v54, vcc, s10, v96
	v_add_u32_e32 v203, v203, v204
	s_nop 0
	v_addc_co_u32_e32 v55, vcc, 0, v97, vcc
	v_add_co_u32_e32 v62, vcc, s12, v94
	v_add_u32_e32 v204, v205, v105
	s_nop 0
	v_addc_co_u32_e32 v63, vcc, 0, v95, vcc
	v_add_co_u32_e32 v70, vcc, s12, v96
	v_add_u32_e32 v231, s25, v125
	s_nop 0
	v_addc_co_u32_e32 v71, vcc, 0, v97, vcc
	v_add_co_u32_e32 v78, vcc, s13, v94
	global_load_dwordx4 v[26:29], v[30:31], off offset:-4096 nt
	s_nop 0
	global_load_dwordx4 v[30:33], v[30:31], off nt
	s_nop 0
	global_load_dwordx4 v[34:37], v[38:39], off offset:-4096 nt
	s_nop 0
	global_load_dwordx4 v[38:41], v[38:39], off nt
	s_nop 0
	global_load_dwordx4 v[42:45], v[46:47], off offset:-4096 nt
	s_nop 0
	global_load_dwordx4 v[46:49], v[46:47], off nt
	s_nop 0
	global_load_dwordx4 v[50:53], v[54:55], off offset:-4096 nt
	s_nop 0
	global_load_dwordx4 v[54:57], v[54:55], off nt
	s_nop 0
	global_load_dwordx4 v[58:61], v[62:63], off offset:-4096 nt
	s_nop 0
	global_load_dwordx4 v[62:65], v[62:63], off nt
	s_nop 0
	global_load_dwordx4 v[66:69], v[70:71], off offset:-4096 nt
	s_nop 0
	global_load_dwordx4 v[70:73], v[70:71], off nt
	v_addc_co_u32_e32 v79, vcc, 0, v95, vcc
	v_add_co_u32_e32 v86, vcc, s13, v96
	v_add_u32_e32 v232, s25, v126
	s_nop 0
	v_addc_co_u32_e32 v87, vcc, 0, v97, vcc
	v_add_co_u32_e32 v98, vcc, s14, v94
	global_load_dwordx4 v[74:77], v[78:79], off offset:-4096 nt
	s_nop 0
	global_load_dwordx4 v[78:81], v[78:79], off nt
	s_nop 0
	global_load_dwordx4 v[82:85], v[86:87], off offset:-4096 nt
	s_nop 0
	global_load_dwordx4 v[86:89], v[86:87], off nt
	v_addc_co_u32_e32 v99, vcc, 0, v95, vcc
	v_add_co_u32_e32 v100, vcc, s14, v96
	v_add_u32_e32 v233, s25, v127
	s_nop 0
	v_addc_co_u32_e32 v101, vcc, 0, v97, vcc
	global_load_dwordx4 v[90:93], v[98:99], off offset:-4096 nt
	global_load_dwordx4 v[106:109], v[98:99], off nt
	global_load_dwordx4 v[110:113], v[100:101], off offset:-4096 nt
	global_load_dwordx4 v[118:121], v[100:101], off nt
	v_add_co_u32_e32 v98, vcc, s15, v94
	v_add_u32_e32 v234, s25, v128
	s_nop 0
	v_addc_co_u32_e32 v99, vcc, 0, v95, vcc
	v_add_co_u32_e32 v100, vcc, s15, v96
	v_add_u32_e32 v235, s25, v129
	s_nop 0
	v_addc_co_u32_e32 v101, vcc, 0, v97, vcc
	global_load_dwordx4 v[138:141], v[98:99], off offset:-4096 nt
	global_load_dwordx4 v[146:149], v[98:99], off nt
	global_load_dwordx4 v[142:145], v[100:101], off offset:-4096 nt
	global_load_dwordx4 v[150:153], v[100:101], off nt
	v_add_co_u32_e32 v98, vcc, s17, v94
	v_add_u32_e32 v236, s25, v130
	s_nop 0
	v_addc_co_u32_e32 v99, vcc, 0, v95, vcc
	v_add_co_u32_e32 v100, vcc, s17, v96
	v_add_u32_e32 v237, s25, v124
	s_nop 0
	v_addc_co_u32_e32 v101, vcc, 0, v97, vcc
	v_add_co_u32_e32 v94, vcc, s18, v94
	global_load_dwordx4 v[154:157], v[98:99], off offset:-4096 nt
	global_load_dwordx4 v[162:165], v[98:99], off nt
	global_load_dwordx4 v[158:161], v[100:101], off offset:-4096 nt
	global_load_dwordx4 v[166:169], v[100:101], off nt
	v_addc_co_u32_e32 v95, vcc, 0, v95, vcc
	global_load_dwordx4 v[170:173], v[94:95], off nt
	v_add_co_u32_e32 v94, vcc, s18, v96
	v_or_b32_e32 v99, 2, v182
	s_nop 0
	v_addc_co_u32_e32 v95, vcc, 0, v97, vcc
	global_load_dwordx4 v[174:177], v[94:95], off nt
	v_lshlrev_b32_e32 v96, 4, v182
	v_lshl_add_u32 v100, v99, 8, s25
	v_lshlrev_b32_e32 v99, 4, v99
	v_and_b32_e32 v94, 0xf8, v103
	v_bitop3_b32 v96, v103, v96, s19 bitop3:0x6c
	v_bitop3_b32 v99, v99, v103, s19 bitop3:0x78
	v_bitop3_b32 v103, v184, v103, s19 bitop3:0x78
	v_lshlrev_b32_e32 v184, 4, v178
	v_bitop3_b32 v178, v178, v104, 3 bitop3:0x6c
	v_lshl_add_u32 v210, v178, 5, v208
	v_or_b32_e32 v178, 20, v182
	v_bitop3_b32 v209, v184, v94, 48 bitop3:0x6c
	v_lshl_add_u32 v211, v178, 8, s25
	v_lshlrev_b32_e32 v184, 4, v178
	v_bitop3_b32 v178, v178, v104, 5 bitop3:0x6c
	v_lshl_add_u32 v213, v178, 5, v211
	v_or_b32_e32 v178, 22, v182
	v_bitop3_b32 v212, v184, v94, s26 bitop3:0x6c
	v_lshl_add_u32 v214, v178, 8, s25
	v_lshlrev_b32_e32 v184, 4, v178
	v_bitop3_b32 v178, v178, v104, 7 bitop3:0x6c
	s_movk_i32 s26, 0x70
	v_lshl_add_u32 v216, v178, 5, v214
	v_or_b32_e32 v178, 24, v182
	v_bitop3_b32 v215, v184, v94, s26 bitop3:0x6c
	v_lshl_add_u32 v217, v178, 8, s25
	v_lshlrev_b32_e32 v178, 4, v178
	s_movk_i32 s26, 0x90
	v_bitop3_b32 v218, v178, v94, s26 bitop3:0x6c
	v_or_b32_e32 v178, 26, v182
	v_lshl_add_u32 v219, v178, 8, s25
	v_lshlrev_b32_e32 v184, 4, v178
	v_bitop3_b32 v178, v178, v104, 3 bitop3:0x6c
	s_movk_i32 s26, 0xb0
	v_lshl_add_u32 v221, v178, 5, v219
	v_or_b32_e32 v178, 28, v182
	v_bitop3_b32 v220, v184, v94, s26 bitop3:0x6c
	v_lshl_add_u32 v227, v178, 8, s25
	v_lshlrev_b32_e32 v184, 4, v178
	v_bitop3_b32 v178, v178, v104, 5 bitop3:0x6c
	v_xor_b32_e32 v97, v182, v104
	s_movk_i32 s26, 0xd0
	v_lshl_add_u32 v229, v178, 5, v227
	v_or_b32_e32 v178, 30, v182
	v_lshl_add_u32 v95, v182, 8, s25
	v_lshlrev_b32_e32 v97, 5, v97
	v_bitop3_b32 v101, v182, v104, 2 bitop3:0x36
	v_bitop3_b32 v228, v184, v94, s26 bitop3:0x6c
	v_lshl_add_u32 v230, v178, 8, s25
	v_lshlrev_b32_e32 v184, 4, v178
	s_movk_i32 s26, 0xf0
	v_bitop3_b32 v104, v178, v104, 7 bitop3:0x6c
	v_add_u32_e32 v98, v95, v97
	v_lshl_add_u32 v101, v101, 5, v100
	v_add_u32_e32 v180, v179, v97
	v_add_u32_e32 v97, v217, v97
	v_bitop3_b32 v94, v184, v94, s26 bitop3:0x6c
	v_lshl_add_u32 v104, v104, 5, v230
	v_lshl_or_b32 v184, v102, 2, s23
	v_mov_b32_e32 v178, 0xf149f2ca
	v_add_u32_e32 v190, v95, v96
	v_add_u32_e32 v191, v98, v105
	v_add_u32_e32 v192, v100, v99
	v_add_u32_e32 v193, v101, v105
	v_add_u32_e32 v200, v180, v105
	v_add_u32_e32 v205, v206, v103
	v_add_u32_e32 v206, v207, v105
	v_add_u32_e32 v207, v208, v209
	v_add_u32_e32 v208, v210, v105
	v_add_u32_e32 v209, v211, v212
	v_add_u32_e32 v210, v213, v105
	v_add_u32_e32 v211, v214, v215
	v_add_u32_e32 v212, v216, v105
	v_add_u32_e32 v213, v217, v218
	v_add_u32_e32 v214, v97, v105
	v_add_u32_e32 v215, v219, v220
	v_add_u32_e32 v216, v221, v105
	v_add_u32_e32 v217, v227, v228
	v_add_u32_e32 v218, v229, v105
	v_add_u32_e32 v219, v230, v94
	v_add_u32_e32 v220, v104, v105
	s_lshl_b32 s23, s23, 2
	v_add_u32_e32 v221, s25, v114
	v_add_u32_e32 v227, s25, v115
	v_add_u32_e32 v228, s25, v116
	v_add_u32_e32 v229, s25, v117
	v_add_u32_e32 v230, v123, v122
	v_mov_b32_e32 v94, 0
	v_mov_b32_e32 v95, v189
	v_mov_b32_e32 v96, v189
	v_mov_b32_e32 v97, v189
	v_mov_b32_e32 v98, 0
	v_mov_b32_e32 v99, v189
	v_mov_b32_e32 v100, v189
	v_mov_b32_e32 v101, v189
	v_mov_b32_e32 v102, 0
	v_mov_b32_e32 v103, v189
	v_mov_b32_e32 v104, v189
	v_mov_b32_e32 v105, v189
	v_mov_b32_e32 v114, 0
	v_mov_b32_e32 v115, v189
	v_mov_b32_e32 v116, v189
	v_mov_b32_e32 v117, v189
	v_mov_b32_e32 v122, 0
	v_mov_b32_e32 v123, v189
	v_mov_b32_e32 v124, v189
	v_mov_b32_e32 v125, v189
	v_mov_b32_e32 v126, 0
	v_mov_b32_e32 v127, v189
	v_mov_b32_e32 v128, v189
	v_mov_b32_e32 v129, v189
	v_mov_b32_e32 v130, 0
	v_mov_b32_e32 v131, v189
	v_mov_b32_e32 v132, v189
	v_mov_b32_e32 v133, v189
	v_mov_b32_e32 v134, 0
	v_mov_b32_e32 v135, v189
	v_mov_b32_e32 v136, v189
	v_mov_b32_e32 v137, v189
.LBB0_596:
	s_waitcnt vmcnt(29)
	v_cvt_pk_bf16_f32 v240, v26, v27
	v_cvt_pk_bf16_f32 v241, v28, v29
	ds_write_b64 v192, v[240:241]
	s_waitcnt vmcnt(27)
	v_cvt_pk_bf16_f32 v240, v34, v35
	v_cvt_pk_bf16_f32 v241, v36, v37
	ds_write_b64 v193, v[240:241] offset:8192
	v_cvt_pk_bf16_f32 v240, v30, v31
	v_cvt_pk_bf16_f32 v241, v32, v33
	ds_write_b64 v194, v[240:241]
	s_waitcnt vmcnt(26)
	v_cvt_pk_bf16_f32 v240, v38, v39
	v_cvt_pk_bf16_f32 v241, v40, v41
	ds_write_b64 v195, v[240:241] offset:8192
	s_waitcnt vmcnt(25)
	v_cvt_pk_bf16_f32 v240, v42, v43
	v_cvt_pk_bf16_f32 v241, v44, v45
	ds_write_b64 v197, v[240:241]
	s_waitcnt vmcnt(23)
	v_cvt_pk_bf16_f32 v240, v50, v51
	v_cvt_pk_bf16_f32 v241, v52, v53
	ds_write_b64 v198, v[240:241] offset:8192
	v_cvt_pk_bf16_f32 v240, v46, v47
	v_cvt_pk_bf16_f32 v241, v48, v49
	ds_write_b64 v199, v[240:241]
	s_waitcnt vmcnt(22)
	v_cvt_pk_bf16_f32 v240, v54, v55
	v_cvt_pk_bf16_f32 v241, v56, v57
	ds_write_b64 v200, v[240:241] offset:8192
	s_waitcnt vmcnt(21)
	v_cvt_pk_bf16_f32 v240, v58, v59
	v_cvt_pk_bf16_f32 v241, v60, v61
	ds_write_b64 v201, v[240:241]
	s_waitcnt vmcnt(19)
	v_cvt_pk_bf16_f32 v240, v66, v67
	v_cvt_pk_bf16_f32 v241, v68, v69
	ds_write_b64 v202, v[240:241] offset:8192
	v_cvt_pk_bf16_f32 v240, v62, v63
	v_cvt_pk_bf16_f32 v241, v64, v65
	ds_write_b64 v203, v[240:241]
	s_waitcnt vmcnt(18)
	v_cvt_pk_bf16_f32 v240, v70, v71
	v_cvt_pk_bf16_f32 v241, v72, v73
	ds_write_b64 v204, v[240:241] offset:8192
	s_waitcnt vmcnt(17)
	v_cvt_pk_bf16_f32 v240, v74, v75
	v_cvt_pk_bf16_f32 v241, v76, v77
	ds_write_b64 v205, v[240:241]
	s_waitcnt vmcnt(15)
	v_cvt_pk_bf16_f32 v240, v82, v83
	v_cvt_pk_bf16_f32 v241, v84, v85
	v_cvt_pk_bf16_f32 v180, v18, v19
	v_cvt_pk_bf16_f32 v181, v20, v21
	ds_write_b64 v206, v[240:241] offset:8192
	v_cvt_pk_bf16_f32 v240, v78, v79
	v_cvt_pk_bf16_f32 v241, v80, v81
	v_cvt_pk_bf16_f32 v238, v22, v23
	v_cvt_pk_bf16_f32 v239, v24, v25
	ds_write2st64_b64 v190, v[180:181], v[240:241] offset1:8
	s_waitcnt vmcnt(14)
	v_cvt_pk_bf16_f32 v180, v86, v87
	v_cvt_pk_bf16_f32 v181, v88, v89
	ds_write2st64_b64 v191, v[238:239], v[180:181] offset0:16 offset1:24
	s_waitcnt vmcnt(13)
	v_cvt_pk_bf16_f32 v180, v90, v91
	v_cvt_pk_bf16_f32 v181, v92, v93
	ds_write_b64 v207, v[180:181]
	s_waitcnt vmcnt(11)
	v_cvt_pk_bf16_f32 v180, v110, v111
	v_cvt_pk_bf16_f32 v181, v112, v113
	ds_write_b64 v208, v[180:181] offset:8192
	v_cvt_pk_bf16_f32 v180, v106, v107
	v_cvt_pk_bf16_f32 v181, v108, v109
	ds_write_b64 v209, v[180:181]
	s_waitcnt vmcnt(10)
	v_cvt_pk_bf16_f32 v180, v118, v119
	v_cvt_pk_bf16_f32 v181, v120, v121
	ds_write_b64 v210, v[180:181] offset:8192
	s_waitcnt vmcnt(9)
	v_cvt_pk_bf16_f32 v180, v138, v139
	v_cvt_pk_bf16_f32 v181, v140, v141
	ds_write_b64 v211, v[180:181]
	s_waitcnt vmcnt(7)
	v_cvt_pk_bf16_f32 v180, v142, v143
	v_cvt_pk_bf16_f32 v181, v144, v145
	ds_write_b64 v212, v[180:181] offset:8192
	v_cvt_pk_bf16_f32 v180, v146, v147
	v_cvt_pk_bf16_f32 v181, v148, v149
	ds_write_b64 v213, v[180:181]
	s_waitcnt vmcnt(6)
	v_cvt_pk_bf16_f32 v180, v150, v151
	v_cvt_pk_bf16_f32 v181, v152, v153
	ds_write_b64 v214, v[180:181] offset:8192
	s_waitcnt vmcnt(5)
	v_cvt_pk_bf16_f32 v180, v154, v155
	v_cvt_pk_bf16_f32 v181, v156, v157
	ds_write_b64 v215, v[180:181]
	s_waitcnt vmcnt(3)
	v_cvt_pk_bf16_f32 v180, v158, v159
	v_cvt_pk_bf16_f32 v181, v160, v161
	ds_write_b64 v216, v[180:181] offset:8192
	v_cvt_pk_bf16_f32 v180, v162, v163
	v_cvt_pk_bf16_f32 v181, v164, v165
	ds_write_b64 v217, v[180:181]
	s_waitcnt vmcnt(2)
	v_cvt_pk_bf16_f32 v180, v166, v167
	v_cvt_pk_bf16_f32 v181, v168, v169
	ds_write_b64 v218, v[180:181] offset:8192
	s_waitcnt vmcnt(1)
	v_cvt_pk_bf16_f32 v180, v170, v171
	v_cvt_pk_bf16_f32 v181, v172, v173
	s_add_i32 s25, s24, 1
	ds_write_b64 v219, v[180:181]
	s_waitcnt vmcnt(0)
	v_cvt_pk_bf16_f32 v180, v174, v175
	v_cvt_pk_bf16_f32 v181, v176, v177
	s_cmp_lg_u32 s24, 15
	ds_write_b64 v220, v[180:181] offset:8192
	s_cbranch_scc0 .LBB0_598
	s_and_b32 s26, s25, -4
	v_mov_b32_e32 v18, s26
	global_load_dword v18, v18, s[0:1]
	s_add_i32 s28, s22, s98
	s_and_b32 s28, s28, 0x60
	s_waitcnt vmcnt(0)
	v_readfirstlane_b32 s26, v18
	s_ashr_i32 s27, s26, 31
	s_lshl_b64 s[26:27], s[26:27], 7
	s_or_b32 s26, s26, s28
	v_mov_b32_e32 v19, s27
	v_or_b32_e32 v18, s26, v182
	v_lshlrev_b64 v[18:19], 11, v[18:19]
	v_lshl_or_b32 v18, v184, 2, v18
	v_lshl_add_u64 v[170:171], s[72:73], 0, v[18:19]
	v_add_co_u32_e32 v30, vcc, s11, v170
	v_lshl_add_u64 v[174:175], s[74:75], 0, v[18:19]
	s_nop 0
	v_addc_co_u32_e32 v31, vcc, 0, v171, vcc
	v_add_co_u32_e32 v38, vcc, s11, v174
	global_load_dwordx4 v[18:21], v[170:171], off nt
	global_load_dwordx4 v[22:25], v[174:175], off nt
	v_addc_co_u32_e32 v39, vcc, 0, v175, vcc
	v_add_co_u32_e32 v46, vcc, s10, v170
	global_load_dwordx4 v[26:29], v[30:31], off offset:-4096 nt
	s_nop 0
	v_addc_co_u32_e32 v47, vcc, 0, v171, vcc
	v_add_co_u32_e32 v54, vcc, s10, v174
	global_load_dwordx4 v[34:37], v[38:39], off offset:-4096 nt
	s_nop 0
	global_load_dwordx4 v[30:33], v[30:31], off nt
	s_nop 0
	global_load_dwordx4 v[38:41], v[38:39], off nt
	v_addc_co_u32_e32 v55, vcc, 0, v175, vcc
	v_add_co_u32_e32 v62, vcc, s12, v170
	global_load_dwordx4 v[42:45], v[46:47], off offset:-4096 nt
	s_nop 0
	v_addc_co_u32_e32 v63, vcc, 0, v171, vcc
	v_add_co_u32_e32 v70, vcc, s12, v174
	global_load_dwordx4 v[50:53], v[54:55], off offset:-4096 nt
	s_nop 0
	global_load_dwordx4 v[46:49], v[46:47], off nt
	s_nop 0
	global_load_dwordx4 v[54:57], v[54:55], off nt
	v_addc_co_u32_e32 v71, vcc, 0, v175, vcc
	v_add_co_u32_e32 v78, vcc, s13, v170
	global_load_dwordx4 v[58:61], v[62:63], off offset:-4096 nt
	s_nop 0
	v_addc_co_u32_e32 v79, vcc, 0, v171, vcc
	v_add_co_u32_e32 v86, vcc, s13, v174
	global_load_dwordx4 v[66:69], v[70:71], off offset:-4096 nt
	s_nop 0
	global_load_dwordx4 v[62:65], v[62:63], off nt
	s_nop 0
	global_load_dwordx4 v[70:73], v[70:71], off nt
	v_addc_co_u32_e32 v87, vcc, 0, v175, vcc
	v_add_co_u32_e32 v106, vcc, s14, v170
	global_load_dwordx4 v[74:77], v[78:79], off offset:-4096 nt
	s_nop 0
	v_addc_co_u32_e32 v107, vcc, 0, v171, vcc
	v_add_co_u32_e32 v118, vcc, s14, v174
	global_load_dwordx4 v[82:85], v[86:87], off offset:-4096 nt
	s_nop 0
	global_load_dwordx4 v[78:81], v[78:79], off nt
	s_nop 0
	global_load_dwordx4 v[86:89], v[86:87], off nt
	v_addc_co_u32_e32 v119, vcc, 0, v175, vcc
	v_add_co_u32_e32 v146, vcc, s15, v170
	global_load_dwordx4 v[90:93], v[106:107], off offset:-4096 nt
	s_nop 0
	v_addc_co_u32_e32 v147, vcc, 0, v171, vcc
	v_add_co_u32_e32 v150, vcc, s15, v174
	global_load_dwordx4 v[110:113], v[118:119], off offset:-4096 nt
	s_nop 0
	global_load_dwordx4 v[106:109], v[106:107], off nt
	s_nop 0
	global_load_dwordx4 v[118:121], v[118:119], off nt
	v_addc_co_u32_e32 v151, vcc, 0, v175, vcc
	v_add_co_u32_e32 v154, vcc, s16, v170
	global_load_dwordx4 v[138:141], v[146:147], off offset:-4096 nt
	s_nop 0
	v_addc_co_u32_e32 v155, vcc, 0, v171, vcc
	v_add_co_u32_e32 v158, vcc, s16, v174
	global_load_dwordx4 v[142:145], v[150:151], off offset:-4096 nt
	s_nop 0
	global_load_dwordx4 v[146:149], v[146:147], off nt
	s_nop 0
	global_load_dwordx4 v[150:153], v[150:151], off nt
	v_addc_co_u32_e32 v159, vcc, 0, v175, vcc
	v_add_co_u32_e32 v162, vcc, 0xe000, v170
	global_load_dwordx4 v[154:157], v[154:155], off nt
	s_nop 0
	v_addc_co_u32_e32 v163, vcc, 0, v171, vcc
	v_add_co_u32_e32 v166, vcc, 0xe000, v174
	global_load_dwordx4 v[158:161], v[158:159], off nt
	s_nop 0
	v_addc_co_u32_e32 v167, vcc, 0, v175, vcc
	v_add_co_u32_e32 v170, vcc, 0xf000, v170
	global_load_dwordx4 v[162:165], v[162:163], off nt
	s_nop 0
	v_addc_co_u32_e32 v171, vcc, 0, v171, vcc
	v_add_co_u32_e32 v174, vcc, 0xf000, v174
	global_load_dwordx4 v[166:169], v[166:167], off nt
	s_nop 0
	v_addc_co_u32_e32 v175, vcc, 0, v175, vcc
	global_load_dwordx4 v[170:173], v[170:171], off nt
	s_nop 0
	global_load_dwordx4 v[174:177], v[174:175], off nt

	.amdhsa_kernel _Z7hyb_fwd4Args
		.amdhsa_group_segment_fixed_size 0
		.amdhsa_private_segment_fixed_size 0
		.amdhsa_kernarg_size 528
		.amdhsa_user_sgpr_count 2
		.amdhsa_user_sgpr_dispatch_ptr 0
		.amdhsa_user_sgpr_queue_ptr 0
		.amdhsa_user_sgpr_kernarg_segment_ptr 1
		.amdhsa_user_sgpr_dispatch_id 0
		.amdhsa_user_sgpr_kernarg_preload_length 0
		.amdhsa_user_sgpr_kernarg_preload_offset 0
		.amdhsa_user_sgpr_private_segment_size 0
		.amdhsa_uses_dynamic_stack 0
		.amdhsa_enable_private_segment 0
		.amdhsa_system_sgpr_workgroup_id_x 1
		.amdhsa_system_sgpr_workgroup_id_y 0
		.amdhsa_system_sgpr_workgroup_id_z 0
		.amdhsa_system_sgpr_workgroup_info 0
		.amdhsa_system_vgpr_workitem_id 0
		.amdhsa_next_free_vgpr 256
		.amdhsa_next_free_sgpr 102
		.amdhsa_accum_offset 256
		.amdhsa_reserve_vcc 1
		.amdhsa_float_round_mode_32 0
		.amdhsa_float_round_mode_16_64 0
		.amdhsa_float_denorm_mode_32 3
		.amdhsa_float_denorm_mode_16_64 3
		.amdhsa_dx10_clamp 1
		.amdhsa_ieee_mode 1
		.amdhsa_fp16_overflow 0
		.amdhsa_tg_split 0
		.amdhsa_exception_fp_ieee_invalid_op 0
		.amdhsa_exception_fp_denorm_src 0
		.amdhsa_exception_fp_ieee_div_zero 0
		.amdhsa_exception_fp_ieee_overflow 0
		.amdhsa_exception_fp_ieee_underflow 0
		.amdhsa_exception_fp_ieee_inexact 0
		.amdhsa_exception_int_div_zero 0
	.end_amdhsa_kernel

amdhsa.kernels:
  - .agpr_count:     0
    .args:
      - .offset:         0
        .size:           272
        .value_kind:     by_value
      - .offset:         272
        .size:           4
        .value_kind:     hidden_block_count_x
      - .offset:         276
        .size:           4
        .value_kind:     hidden_block_count_y
      - .offset:         280
        .size:           4
        .value_kind:     hidden_block_count_z
      - .offset:         284
        .size:           2
        .value_kind:     hidden_group_size_x
      - .offset:         286
        .size:           2
        .value_kind:     hidden_group_size_y
      - .offset:         288
        .size:           2
        .value_kind:     hidden_group_size_z
      - .offset:         290
        .size:           2
        .value_kind:     hidden_remainder_x
      - .offset:         292
        .size:           2
        .value_kind:     hidden_remainder_y
      - .offset:         294
        .size:           2
        .value_kind:     hidden_remainder_z
      - .offset:         312
        .size:           8
        .value_kind:     hidden_global_offset_x
      - .offset:         320
        .size:           8
        .value_kind:     hidden_global_offset_y
      - .offset:         328
        .size:           8
        .value_kind:     hidden_global_offset_z
      - .offset:         336
        .size:           2
        .value_kind:     hidden_grid_dims
      - .offset:         392
        .size:           4
        .value_kind:     hidden_dynamic_lds_size
    .group_segment_fixed_size: 0
    .kernarg_segment_align: 8
    .kernarg_segment_size: 528
    .language:       OpenCL C
    .language_version:
      - 2
      - 0
    .max_flat_workgroup_size: 512
    .name:           _Z7hyb_fwd4Args
    .private_segment_fixed_size: 0
    .sgpr_count:     108
    .sgpr_spill_count: 141
    .symbol:         _Z7hyb_fwd4Args.kd
    .uniform_work_group_size: 1
    .uses_dynamic_stack: false
    .vgpr_count:     256
    .vgpr_spill_count: 0
    .wavefront_size: 64
